# up2 q epilogue: rope cos/sin loads of the second row of each trip prefetched with the first row's (one dependent round trip per two rows)
# speedup vs baseline: 1.0137x; 1.0137x over previous
.LBB0_450:
	s_waitcnt lgkmcnt(0)
	v_add_u32_e32 v128, 0xffffff80, v188
	ds_read_b32 v148, v128
	ds_read_b128 v[132:135], v186
	ds_read_b128 v[128:131], v186 offset:16
	v_cndmask_b32_e64 v147, 0, 1, s[24:25]
	v_add_u32_e32 v146, s63, v149
	v_cmp_ne_u32_e64 s[8:9], 1, v147
	s_andn2_b64 vcc, exec, s[24:25]
	s_mov_b64 s[0:1], -1
	s_cbranch_vccnz .LBB0_454
	s_waitcnt lgkmcnt(0)
	v_mov_b32_e32 v150, v128
	v_mov_b32_e32 v151, v129
	v_mov_b32_e32 v152, v130
	v_mov_b32_e32 v153, v131
	v_mov_b32_e32 v154, v132
	v_mov_b32_e32 v155, v133
	v_mov_b32_e32 v156, v134
	v_mov_b32_e32 v157, v135
	s_and_saveexec_b64 s[0:1], s[28:29]
	s_cbranch_execz .LBB0_453
	v_add_u32_e32 v147, s63, v168
	v_add_u32_e32 v147, 0xffffff00, v147
	v_ashrrev_i32_e32 v147, 6, v147
	v_cndmask_b32_e64 v147, v163, v147, s[4:5]
	v_lshlrev_b32_e32 v150, 4, v147
	v_ashrrev_i32_e32 v151, 31, v150
	v_lshl_add_u64 v[198:199], v[150:151], 3, v[138:139]
	global_load_dwordx4 v[150:153], v[198:199], off
	global_load_dwordx4 v[192:195], v[198:199], off offset:32
	global_load_dwordx4 v[154:157], v[198:199], off offset:16
	s_nop 0
	global_load_dwordx4 v[198:201], v[198:199], off offset:48
	v_add_u32_e32 v236, s63, v168
	v_add_u32_e32 v236, 0xffffff20, v236
	v_ashrrev_i32_e32 v236, 6, v236
	v_cndmask_b32_e64 v236, v164, v236, s[4:5]
	v_lshlrev_b32_e32 v238, 4, v236
	v_ashrrev_i32_e32 v239, 31, v238
	v_lshl_add_u64 v[240:241], v[238:239], 3, v[138:139]
	global_load_dwordx4 v[220:223], v[240:241], off
	global_load_dwordx4 v[224:227], v[240:241], off offset:32
	global_load_dwordx4 v[228:231], v[240:241], off offset:16
	global_load_dwordx4 v[232:235], v[240:241], off offset:48
	ds_read_b128 v[204:207], v187
	ds_read_b128 v[208:211], v187 offset:16
	v_mov_b32_e32 v212, v135
	v_mov_b32_e32 v214, v131
	s_waitcnt lgkmcnt(1)
	v_mul_f32_e32 v147, v136, v206
	v_mul_f32_e32 v213, v136, v207
	s_waitcnt lgkmcnt(0)
	v_mul_f32_e32 v215, v136, v211
	v_mul_f32_e32 v189, v136, v210
	v_pk_mul_f32 v[204:205], v[136:137], v[204:205]
	v_pk_mul_f32 v[208:209], v[136:137], v[208:209]
	s_waitcnt vmcnt(7)
	v_mov_b32_e32 v206, v150
	v_mov_b32_e32 v207, v152
	v_mov_b32_e32 v152, v151
	s_waitcnt vmcnt(6)
	v_mov_b32_e32 v150, v192
	v_mov_b32_e32 v151, v194
	s_waitcnt vmcnt(5)
	v_mul_f32_e32 v192, v134, v154
	v_mul_f32_e32 v210, v147, v155
	v_pk_mul_f32 v[154:155], v[212:213], v[156:157]
	s_waitcnt vmcnt(4)
	v_pk_mul_f32 v[156:157], v[214:215], v[200:201]
	v_mov_b32_e32 v194, v193
	v_mul_f32_e32 v198, v130, v198
	v_mul_f32_e32 v216, v189, v199
	v_pk_mul_f32 v[200:201], v[132:133], v[206:207]
	v_pk_mul_f32 v[150:151], v[128:129], v[150:151]
	v_mov_b32_e32 v211, v155
	v_mov_b32_e32 v193, v154
	v_mov_b32_e32 v217, v157
	v_mov_b32_e32 v199, v156
	v_pk_fma_f32 v[154:155], v[204:205], v[152:153], v[200:201]
	v_pk_add_f32 v[156:157], v[210:211], v[192:193]
	v_pk_fma_f32 v[150:151], v[208:209], v[194:195], v[150:151]
	v_pk_add_f32 v[152:153], v[216:217], v[198:199]

.LBB0_456:
	s_waitcnt lgkmcnt(2)
	ds_read_b32 v148, v188
	s_waitcnt lgkmcnt(2)
	ds_read_b128 v[132:135], v186 offset:16384
	s_waitcnt lgkmcnt(2)
	ds_read_b128 v[128:131], v186 offset:16400
	v_add_u32_e32 v146, 32, v146
	s_and_b64 vcc, exec, s[8:9]
	s_mov_b64 s[0:1], -1
	s_cbranch_vccnz .LBB0_460
	s_waitcnt lgkmcnt(0)
	v_mov_b32_e32 v150, v128
	v_mov_b32_e32 v151, v129
	v_mov_b32_e32 v152, v130
	v_mov_b32_e32 v153, v131
	v_mov_b32_e32 v154, v132
	v_mov_b32_e32 v155, v133
	v_mov_b32_e32 v156, v134
	v_mov_b32_e32 v157, v135
	s_and_saveexec_b64 s[0:1], s[28:29]
	s_cbranch_execz .LBB0_459
	s_waitcnt vmcnt(1)
	v_mov_b32_e32 v150, v220
	v_mov_b32_e32 v151, v221
	v_mov_b32_e32 v152, v222
	v_mov_b32_e32 v153, v223
	v_mov_b32_e32 v192, v224
	v_mov_b32_e32 v193, v225
	v_mov_b32_e32 v194, v226
	v_mov_b32_e32 v195, v227
	v_mov_b32_e32 v154, v228
	v_mov_b32_e32 v155, v229
	v_mov_b32_e32 v156, v230
	v_mov_b32_e32 v157, v231
	v_mov_b32_e32 v198, v232
	v_mov_b32_e32 v199, v233
	v_mov_b32_e32 v200, v234
	v_mov_b32_e32 v201, v235
	ds_read_b128 v[204:207], v187 offset:16384
	ds_read_b128 v[208:211], v187 offset:16400
	v_mov_b32_e32 v212, v135
	v_mov_b32_e32 v214, v131
	s_waitcnt lgkmcnt(1)
	v_mul_f32_e32 v147, v136, v206
	v_mul_f32_e32 v213, v136, v207
	s_waitcnt lgkmcnt(0)
	v_mul_f32_e32 v215, v136, v211
	v_mul_f32_e32 v189, v136, v210
	v_pk_mul_f32 v[204:205], v[136:137], v[204:205]
	v_pk_mul_f32 v[208:209], v[136:137], v[208:209]
	v_mov_b32_e32 v206, v150
	v_mov_b32_e32 v207, v152
	v_mov_b32_e32 v152, v151
	v_mov_b32_e32 v150, v192
	v_mov_b32_e32 v151, v194
	v_mul_f32_e32 v192, v134, v154
	v_mul_f32_e32 v210, v147, v155
	v_pk_mul_f32 v[154:155], v[212:213], v[156:157]
	v_pk_mul_f32 v[156:157], v[214:215], v[200:201]
	v_mov_b32_e32 v194, v193
	v_mul_f32_e32 v198, v130, v198
	v_mul_f32_e32 v216, v189, v199
	v_pk_mul_f32 v[200:201], v[132:133], v[206:207]
	v_pk_mul_f32 v[150:151], v[128:129], v[150:151]
	v_mov_b32_e32 v211, v155
	v_mov_b32_e32 v193, v154
	v_mov_b32_e32 v217, v157
	v_mov_b32_e32 v199, v156
	v_pk_fma_f32 v[154:155], v[204:205], v[152:153], v[200:201]
	v_pk_add_f32 v[156:157], v[210:211], v[192:193]
	v_pk_fma_f32 v[150:151], v[208:209], v[194:195], v[150:151]
	v_pk_add_f32 v[152:153], v[216:217], v[198:199]

.LBB0_467:
	s_nop 0
	v_add_u32_e32 v0, 0xffffff80, v12
	ds_read_b32 v15, v0
	ds_read_b128 v[4:7], v10
	ds_read_b128 v[0:3], v10 offset:16
	v_add_u32_e32 v13, s8, v168
	s_and_saveexec_b64 s[0:1], s[6:7]
	s_cbranch_execz .LBB0_469
	v_add_u32_e32 v14, 0xffffff00, v13
	v_ashrrev_i32_e32 v14, 6, v14
	v_cndmask_b32_e64 v14, v163, v14, s[4:5]
	v_lshlrev_b32_e32 v16, 4, v14
	v_ashrrev_i32_e32 v17, 31, v16
	v_lshl_add_u64 v[28:29], v[16:17], 3, v[138:139]
	global_load_dwordx4 v[16:19], v[28:29], off
	global_load_dwordx4 v[20:23], v[28:29], off offset:32
	global_load_dwordx4 v[24:27], v[28:29], off offset:16
	s_nop 0
	global_load_dwordx4 v[28:31], v[28:29], off offset:48
	v_add_u32_e32 v236, 0xffffff20, v13
	v_ashrrev_i32_e32 v236, 6, v236
	v_cndmask_b32_e64 v236, v164, v236, s[4:5]
	v_lshlrev_b32_e32 v238, 4, v236
	v_ashrrev_i32_e32 v239, 31, v238
	v_lshl_add_u64 v[240:241], v[238:239], 3, v[138:139]
	global_load_dwordx4 v[220:223], v[240:241], off
	global_load_dwordx4 v[224:227], v[240:241], off offset:32
	global_load_dwordx4 v[228:231], v[240:241], off offset:16
	global_load_dwordx4 v[232:235], v[240:241], off offset:48
	ds_read_b128 v[32:35], v11
	ds_read_b128 v[36:39], v11 offset:16
	s_waitcnt lgkmcnt(3)
	v_mov_b32_e32 v40, v7
	s_waitcnt lgkmcnt(2)
	v_mov_b32_e32 v42, v3
	s_waitcnt lgkmcnt(1)
	v_mul_f32_e32 v41, v136, v35
	s_waitcnt lgkmcnt(0)
	v_mul_f32_e32 v7, v136, v38
	v_mul_f32_e32 v43, v136, v39
	v_mul_f32_e32 v3, v136, v34
	v_pk_mul_f32 v[32:33], v[136:137], v[32:33]
	v_pk_mul_f32 v[36:37], v[136:137], v[36:37]
	s_waitcnt vmcnt(7)
	v_mov_b32_e32 v34, v16
	v_mov_b32_e32 v35, v18
	v_mov_b32_e32 v18, v17
	s_waitcnt vmcnt(6)
	v_mov_b32_e32 v16, v20
	v_mov_b32_e32 v17, v22
	s_waitcnt vmcnt(5)
	v_mul_f32_e32 v6, v6, v24
	s_waitcnt vmcnt(4)
	v_mul_f32_e32 v2, v2, v28
	v_mul_f32_e32 v24, v7, v29
	v_pk_mul_f32 v[26:27], v[40:41], v[26:27]
	v_pk_mul_f32 v[28:29], v[42:43], v[30:31]
	v_mov_b32_e32 v22, v21
	v_mul_f32_e32 v20, v3, v25
	v_pk_mul_f32 v[4:5], v[4:5], v[34:35]
	v_pk_mul_f32 v[0:1], v[0:1], v[16:17]
	v_mov_b32_e32 v21, v27
	v_mov_b32_e32 v7, v26
	v_mov_b32_e32 v25, v29
	v_mov_b32_e32 v3, v28
	v_pk_fma_f32 v[4:5], v[32:33], v[18:19], v[4:5]
	v_pk_add_f32 v[6:7], v[20:21], v[6:7]
	v_pk_fma_f32 v[0:1], v[36:37], v[22:23], v[0:1]
	v_pk_add_f32 v[2:3], v[24:25], v[2:3]
.LBB0_469:
	s_or_b64 exec, exec, s[0:1]
	s_waitcnt lgkmcnt(2)
	v_mul_f32_e32 v16, 0x3dd53b94, v15
	v_add_u32_e32 v14, s8, v149
	s_waitcnt lgkmcnt(1)
	v_pk_mul_f32 v[6:7], v[16:17], v[6:7] op_sel_hi:[0,1]
	v_pk_mul_f32 v[4:5], v[16:17], v[4:5] op_sel_hi:[0,1]
	s_waitcnt lgkmcnt(0)
	v_pk_mul_f32 v[18:19], v[16:17], v[2:3] op_sel_hi:[0,1]
	v_pk_mul_f32 v[2:3], v[16:17], v[0:1] op_sel_hi:[0,1]
	v_cvt_pk_bf16_f32 v0, v4, v5
	v_cvt_pk_bf16_f32 v1, v6, v7
	v_cvt_pk_bf16_f32 v2, v2, v3
	v_cvt_pk_bf16_f32 v3, v18, v19
	v_mad_i64_i32 v[4:5], s[0:1], v14, s84, v[8:9]
	global_store_dwordx4 v[4:5], v[0:3], off
	ds_read_b32 v15, v12
	ds_read_b128 v[4:7], v10 offset:16384
	ds_read_b128 v[0:3], v10 offset:16400
	s_and_saveexec_b64 s[0:1], s[6:7]
	s_cbranch_execz .LBB0_466
	s_waitcnt vmcnt(1)
	v_mov_b32_e32 v16, v220
	v_mov_b32_e32 v17, v221
	v_mov_b32_e32 v18, v222
	v_mov_b32_e32 v19, v223
	v_mov_b32_e32 v20, v224
	v_mov_b32_e32 v21, v225
	v_mov_b32_e32 v22, v226
	v_mov_b32_e32 v23, v227
	v_mov_b32_e32 v24, v228
	v_mov_b32_e32 v25, v229
	v_mov_b32_e32 v26, v230
	v_mov_b32_e32 v27, v231
	v_mov_b32_e32 v28, v232
	v_mov_b32_e32 v29, v233
	v_mov_b32_e32 v30, v234
	v_mov_b32_e32 v31, v235
	ds_read_b128 v[32:35], v11 offset:16384
	ds_read_b128 v[36:39], v11 offset:16400
	s_waitcnt lgkmcnt(3)
	v_mov_b32_e32 v40, v7
	s_waitcnt lgkmcnt(2)
	v_mov_b32_e32 v42, v3
	s_waitcnt lgkmcnt(1)
	v_mul_f32_e32 v41, v136, v35
	s_waitcnt lgkmcnt(0)
	v_mul_f32_e32 v7, v136, v38
	v_mul_f32_e32 v43, v136, v39
	v_mul_f32_e32 v3, v136, v34
	v_pk_mul_f32 v[32:33], v[136:137], v[32:33]
	v_pk_mul_f32 v[36:37], v[136:137], v[36:37]
	v_mov_b32_e32 v34, v16
	v_mov_b32_e32 v35, v18
	v_mov_b32_e32 v18, v17
	v_mov_b32_e32 v16, v20
	v_mov_b32_e32 v17, v22
	v_mul_f32_e32 v6, v6, v24
	v_mul_f32_e32 v2, v2, v28
	v_mul_f32_e32 v24, v7, v29
	v_pk_mul_f32 v[26:27], v[40:41], v[26:27]
	v_pk_mul_f32 v[28:29], v[42:43], v[30:31]
	v_mov_b32_e32 v22, v21
	v_mul_f32_e32 v20, v3, v25
	v_pk_mul_f32 v[4:5], v[4:5], v[34:35]
	v_pk_mul_f32 v[0:1], v[0:1], v[16:17]
	v_mov_b32_e32 v21, v27
	v_mov_b32_e32 v7, v26
	v_mov_b32_e32 v25, v29
	v_mov_b32_e32 v3, v28
	v_pk_fma_f32 v[4:5], v[32:33], v[18:19], v[4:5]
	v_pk_add_f32 v[6:7], v[20:21], v[6:7]
	v_pk_fma_f32 v[0:1], v[36:37], v[22:23], v[0:1]
	v_pk_add_f32 v[2:3], v[24:25], v[2:3]
	s_branch .LBB0_466
